# G1 KK tile loop rewritten branch-free: all LDS reads of a tile up front, masks via v_cndmask instead of 8 exec-masked branches
# speedup vs baseline: 1.0290x; 1.0045x over previous
; #define LAS __attribute__((address_space(3)))
; #define MFMA16(a, b, c) __builtin_amdgcn_mfma_f32_16x16x32_bf16((a), (b), (c), 0, 0, 0)
; __device__ NOINL void g1_phase(const LAS Params* lp, int l, LAS unsigned char* lds) {
;     ...
;         for (int q = 0; q < 6; ++q) {
;             const int tix = w * 6 + q, s = tix >> 4, itl = (tix >> 2) & 3, jt = tix & 3;
;             const LAS bf16_t* Kn = (const LAS bf16_t*)(lds + s * SLOT);
;             const LAS float* gcs = (const LAS float*)(lds + s * SLOT + 17408);
;             LAS float* Lm = (LAS float*)(lds + s * SLOT + 18432);
;             f32x4 acc = {0.f, 0.f, 0.f, 0.f};
; #pragma unroll
;             for (int ks = 0; ks < 4; ++ks) {
;                 const bf16x8 A = *(const LAS bf16x8*)(Kn + (16 * itl + fr) * 136 + ks * 32 + fq * 8), B = *(const LAS bf16x8*)(Kn + (16 * jt + fr) * 136 + ks * 32 + fq * 8);
;                 acc = MFMA16(A, B, acc);
;             }
;             const int jj = 16 * jt + fr;
; #pragma unroll
;             for (int j = 0; j < 4; ++j) {
;                 const int i = 16 * itl + 4 * fq + j;
;                 const float v0 = jj < i ? gcs[128 + i] * acc[j] * __expf(gcs[i] - gcs[jj]) : 0.f;
;                 const int p1 = 63 - i, pp1 = 63 - jj;
;                 const float v1 = jj > i ? gcs[192 + p1] * acc[j] * __expf(gcs[64 + p1] - gcs[64 + pp1]) : 0.f;
;                 Lm[i * 64 + jj] = v0; Lm[4096 + p1 * 64 + pp1] = v1;
;             }
;         }
.LBB0_1049:
	v_add_u32_e32 v103, s0, v27
	v_lshrrev_b32_e32 v8, 4, v103
	v_mul_lo_u32 v8, v8, s26
	v_add_u32_e32 v101, 0, v8
	v_and_or_b32 v8, v99, 48, v3
	v_mul_u32_u24_e32 v8, 0x110, v8
	v_and_or_b32 v102, v100, 48, v3
	v_add3_u32 v112, v101, v8, v98
	v_mad_u32_u24 v113, v102, s35, v101
	v_add_u32_e32 v114, v113, v98
	s_waitcnt lgkmcnt(0)
	ds_read_b128 v[116:119], v112
	ds_read_b128 v[132:135], v114
	ds_read_b128 v[120:123], v112 offset:64
	ds_read_b128 v[136:139], v114 offset:64
	ds_read_b128 v[124:127], v112 offset:128
	ds_read_b128 v[140:143], v114 offset:128
	ds_read_b128 v[128:131], v112 offset:192
	ds_read_b128 v[144:147], v114 offset:192
	v_and_or_b32 v110, v103, 12, v20
	v_lshlrev_b32_e32 v104, 2, v110
	s_movk_i32 s1, 0xfef4
	v_mad_i32_i24 v103, v102, s1, v113
	v_lshl_add_u32 v107, v104, 2, v101
	v_xor_b32_e32 v105, 63, v102
	v_xor_b32_e32 v108, 60, v104
	v_lshl_add_u32 v106, v105, 2, v101
	v_lshl_add_u32 v108, v108, 2, v101
	ds_read_b32 v148, v103 offset:17408
	ds_read_b128 v[152:155], v107 offset:17408
	ds_read_b128 v[156:159], v107 offset:17920
	ds_read_b32 v149, v106 offset:17664
	ds_read_b128 v[160:163], v108 offset:17664
	ds_read_b128 v[164:167], v108 offset:18176
	s_waitcnt lgkmcnt(12)
	v_mfma_f32_16x16x32_bf16 v[8:11], v[116:119], v[132:135], 0
	s_waitcnt lgkmcnt(10)
	v_mfma_f32_16x16x32_bf16 v[8:11], v[120:123], v[136:139], v[8:11]
	s_waitcnt lgkmcnt(8)
	v_mfma_f32_16x16x32_bf16 v[8:11], v[124:127], v[140:143], v[8:11]
	s_waitcnt lgkmcnt(6)
	v_mfma_f32_16x16x32_bf16 v[8:11], v[128:131], v[144:147], v[8:11]
	v_or_b32_e32 v109, 1, v104
	v_or_b32_e32 v111, 2, v104
	v_or_b32_e32 v115, 3, v104
	s_waitcnt lgkmcnt(3)
	v_sub_f32_e32 v116, v152, v148
	v_sub_f32_e32 v117, v153, v148
	v_sub_f32_e32 v118, v154, v148
	v_sub_f32_e32 v119, v155, v148
	v_mul_f32_e32 v116, 0x3fb8aa3b, v116
	v_mul_f32_e32 v117, 0x3fb8aa3b, v117
	v_mul_f32_e32 v118, 0x3fb8aa3b, v118
	v_mul_f32_e32 v119, 0x3fb8aa3b, v119
	v_exp_f32_e32 v116, v116
	v_exp_f32_e32 v117, v117
	v_exp_f32_e32 v118, v118
	v_exp_f32_e32 v119, v119
	s_waitcnt lgkmcnt(0)
	v_sub_f32_e32 v120, v163, v149
	v_sub_f32_e32 v121, v162, v149
	v_sub_f32_e32 v122, v161, v149
	v_sub_f32_e32 v123, v160, v149
	v_mul_f32_e32 v120, 0x3fb8aa3b, v120
	v_mul_f32_e32 v121, 0x3fb8aa3b, v121
	v_mul_f32_e32 v122, 0x3fb8aa3b, v122
	v_mul_f32_e32 v123, 0x3fb8aa3b, v123
	v_exp_f32_e32 v120, v120
	v_exp_f32_e32 v121, v121
	v_exp_f32_e32 v122, v122
	v_exp_f32_e32 v123, v123
	v_lshl_add_u32 v124, v104, 8, v103
	v_lshl_add_u32 v125, v109, 8, v103
	v_lshl_add_u32 v126, v111, 8, v103
	v_lshl_add_u32 v127, v115, 8, v103
	v_lshlrev_b32_e32 v128, 6, v104
	v_lshlrev_b32_e32 v129, 6, v109
	v_lshlrev_b32_e32 v130, 6, v111
	v_lshlrev_b32_e32 v131, 6, v115
	v_sub_u32_e32 v128, v105, v128
	v_sub_u32_e32 v129, v105, v129
	v_sub_u32_e32 v130, v105, v130
	v_sub_u32_e32 v131, v105, v131
	v_lshl_add_u32 v128, v128, 2, v101
	v_lshl_add_u32 v129, v129, 2, v101
	v_lshl_add_u32 v130, v130, 2, v101
	v_lshl_add_u32 v131, v131, 2, v101
	v_mul_f32_e32 v132, v8, v156
	v_mul_f32_e32 v133, v9, v157
	v_mul_f32_e32 v134, v10, v158
	v_mul_f32_e32 v135, v11, v159
	v_mul_f32_e32 v136, v8, v167
	v_mul_f32_e32 v137, v9, v166
	v_mul_f32_e32 v138, v10, v165
	v_mul_f32_e32 v139, v11, v164
	v_mul_f32_e32 v132, v132, v116
	v_mul_f32_e32 v133, v133, v117
	v_mul_f32_e32 v134, v134, v118
	v_mul_f32_e32 v135, v135, v119
	v_mul_f32_e32 v136, v136, v120
	v_mul_f32_e32 v137, v137, v121
	v_mul_f32_e32 v138, v138, v122
	v_mul_f32_e32 v139, v139, v123
	v_cmp_lt_u32_e64 s[56:57], v102, v104
	v_cmp_gt_u32_e64 s[58:59], v102, v104
	s_nop 1
	v_cndmask_b32_e64 v132, 0, v132, s[56:57]
	v_cndmask_b32_e64 v136, 0, v136, s[58:59]
	ds_write_b32 v124, v132 offset:18432
	ds_write_b32 v128, v136 offset:50944
	v_cmp_lt_u32_e64 s[40:41], v102, v109
	v_cmp_gt_u32_e64 s[56:57], v102, v109
	s_nop 1
	v_cndmask_b32_e64 v133, 0, v133, s[40:41]
	v_cndmask_b32_e64 v137, 0, v137, s[56:57]
	ds_write_b32 v125, v133 offset:18432
	ds_write_b32 v129, v137 offset:50944
	v_cmp_lt_u32_e64 s[58:59], v102, v111
	v_cmp_gt_u32_e64 s[40:41], v102, v111
	s_nop 1
	v_cndmask_b32_e64 v134, 0, v134, s[58:59]
	v_cndmask_b32_e64 v138, 0, v138, s[40:41]
	ds_write_b32 v126, v134 offset:18432
	ds_write_b32 v130, v138 offset:50944
	v_cmp_lt_u32_e64 s[56:57], v102, v115
	v_cmp_gt_u32_e64 s[58:59], v102, v115
	s_nop 1
	v_cndmask_b32_e64 v135, 0, v135, s[56:57]
	v_cndmask_b32_e64 v139, 0, v139, s[58:59]
	ds_write_b32 v127, v135 offset:18432
	ds_write_b32 v131, v139 offset:50944
	s_add_i32 s0, s0, 1
	v_add_u32_e32 v100, 16, v100
	v_add_u32_e32 v99, 4, v99
	s_cmp_eq_u32 s0, 6
	s_cbranch_scc0 .LBB0_1049
